# w1 + attention unit epilogue de-serialised: 7 subln loads issued together, counted vmcnt(6) waits instead of vmcnt(0) per load/store pair
# speedup vs baseline: 1.0220x; 1.0060x over previous
; __device__ __forceinline__ void attn_pv(unsigned vaddr, const int (&vo)[8], const bf16x8 (&pf)[2][2], f32x4 (&o)[2][8], f32x4 (&ol)[2]) {
;     s16x4 r[3][4];
;     ...
;     AT_TR4(0, 0); AT_TR4(1, 1);
;     { const bf16x8 ones = (bf16x8){0x3f80, 0x3f80, 0x3f80, 0x3f80, 0x3f80, 0x3f80, 0x3f80, 0x3f80};
; #pragma unroll
;       for (int c = 0; c < 2; ++c)
; #pragma unroll
;           for (int si = 0; si < 2; ++si) ol[c] = __builtin_amdgcn_mfma_f32_16x16x32_bf16(ones, pf[c][si], ol[c], 0, 0, 0); }
; #pragma unroll
;     for (int dt = 0; dt < 8; ++dt) {
;         const int cb = dt % 3;
;         if (dt < 6) { AT_TR4((dt + 2) % 3, dt + 2); asm volatile("s_waitcnt lgkmcnt(8)" : "+v"(r[cb][0]), "+v"(r[cb][1]), "+v"(r[cb][2]), "+v"(r[cb][3])); }
;         else if (dt == 6) asm volatile("s_waitcnt lgkmcnt(4)" : "+v"(r[cb][0]), "+v"(r[cb][1]), "+v"(r[cb][2]), "+v"(r[cb][3]));
;         else asm volatile("s_waitcnt lgkmcnt(0)" : "+v"(r[cb][0]), "+v"(r[cb][1]), "+v"(r[cb][2]), "+v"(r[cb][3]));
; #pragma unroll
;         for (int si = 0; si < 2; ++si) {
;             const s16x4 lo = r[cb][2 * si], hi = r[cb][2 * si + 1];
;             const bf16x8 vf = (bf16x8){lo[0], lo[1], lo[2], lo[3], hi[0], hi[1], hi[2], hi[3]};
;             o[0][dt] = __builtin_amdgcn_mfma_f32_16x16x32_bf16(vf, pf[0][si], o[0][dt], 0, 0, 0);
;             o[1][dt] = __builtin_amdgcn_mfma_f32_16x16x32_bf16(vf, pf[1][si], o[1][dt], 0, 0, 0);
;         }
;     }
;     ...
; }
; template <bool QK, bool PV> ...
;     ...
;     if constexpr (PV) { AT_TR4(0, 0); AT_TR4(1, 1);
;         const bf16x8 ones = (bf16x8){0x3f80, 0x3f80, 0x3f80, 0x3f80, 0x3f80, 0x3f80, 0x3f80, 0x3f80};
; #pragma unroll
;         for (int c = 0; c < 2; ++c)
; #pragma unroll
;             for (int si = 0; si < 2; ++si) ol[c] = __builtin_amdgcn_mfma_f32_16x16x32_bf16(ones, pf[c][si], ol[c], 0, 0, 0); }
; #pragma unroll
;     for (int dt = 0; dt < 8; ++dt) {
;         if constexpr (PV) {
;             const int cb = dt % 3;
;             if (dt < 6) { AT_TR4((dt + 2) % 3, dt + 2); asm volatile("s_waitcnt lgkmcnt(8)" : "+v"(r[cb][0]), "+v"(r[cb][1]), "+v"(r[cb][2]), "+v"(r[cb][3])); }
;             else if (dt == 6) asm volatile("s_waitcnt lgkmcnt(4)" : "+v"(r[cb][0]), "+v"(r[cb][1]), "+v"(r[cb][2]), "+v"(r[cb][3]));
;             else asm volatile("s_waitcnt lgkmcnt(0)" : "+v"(r[cb][0]), "+v"(r[cb][1]), "+v"(r[cb][2]), "+v"(r[cb][3]));
; #pragma unroll
.Lat_yskip_s:
	v_mov_b64_e32 v[140:141], s[6:7]
	v_mov_b64_e32 v[138:139], s[4:5]
	ds_read_b64_tr_b16 v[2:3], v194 offset:0
	ds_read_b64_tr_b16 v[4:5], v194 offset:0x1000
	ds_read_b64_tr_b16 v[10:11], v194 offset:0x2000
	ds_read_b64_tr_b16 v[12:13], v194 offset:0x3000
	v_exp_f32_e32 v154, v74
	s_nop 0
	v_mfma_f32_16x16x32_bf16 v[6:9], v[138:141], v[58:61], v[134:137]
	v_exp_f32_e32 v161, v75
	v_exp_f32_e32 v90, v90
	v_exp_f32_e32 v91, v91
	v_mfma_f32_16x16x32_bf16 v[134:137], v[138:141], v[34:37], v[6:9]
	ds_read_b64_tr_b16 v[6:7], v195 offset:0
	ds_read_b64_tr_b16 v[8:9], v195 offset:0x1000
	ds_read_b64_tr_b16 v[14:15], v195 offset:0x2000
	ds_read_b64_tr_b16 v[16:17], v195 offset:0x3000
	ds_read_b64_tr_b16 v[142:143], v196 offset:0
	ds_read_b64_tr_b16 v[144:145], v196 offset:0x1000
	ds_read_b64_tr_b16 v[146:147], v196 offset:0x2000
	ds_read_b64_tr_b16 v[148:149], v196 offset:0x3000
	s_waitcnt lgkmcnt(8)
	ds_read_b64_tr_b16 v[150:151], v197 offset:0
	ds_read_b64_tr_b16 v[152:153], v197 offset:0x1000
	v_mfma_f32_16x16x32_bf16 v[130:133], v[138:141], v[42:45], v[130:133]
	v_exp_f32_e32 v92, v92
	v_exp_f32_e32 v93, v93
	v_exp_f32_e32 v94, v94
	v_mfma_f32_16x16x32_bf16 v[126:129], v[2:5], v[58:61], v[126:129]
	v_exp_f32_e32 v95, v95
	v_exp_f32_e32 v96, v96
	v_exp_f32_e32 v97, v97
	v_mfma_f32_16x16x32_bf16 v[2:5], v[2:5], v[42:45], v[122:125]
	v_exp_f32_e32 v38, v38
	v_exp_f32_e32 v39, v39
	v_exp_f32_e32 v40, v40
	v_mfma_f32_16x16x32_bf16 v[122:125], v[10:13], v[34:37], v[126:129]
	v_exp_f32_e32 v41, v41
	v_exp_f32_e32 v62, v62
	v_exp_f32_e32 v63, v63
	v_mfma_f32_16x16x32_bf16 v[126:129], v[10:13], v[18:21], v[2:5]
	ds_read_b64_tr_b16 v[2:3], v197 offset:0x2000
	ds_read_b64_tr_b16 v[4:5], v197 offset:0x3000
	s_waitcnt lgkmcnt(8)
	v_mfma_f32_16x16x32_bf16 v[130:133], v[138:141], v[18:21], v[130:133]
	v_cvt_pk_bf16_f32 v38, v38, v39
	v_cvt_pk_bf16_f32 v39, v40, v41
	v_cvt_pk_bf16_f32 v40, v62, v63
	v_mfma_f32_16x16x32_bf16 v[10:13], v[6:9], v[58:61], v[114:117]
	s_add_i32 s44, s44, s30
	s_add_i32 s43, s43, s30
	s_cmpk_gt_i32 s44, 0x1ff
	v_mfma_f32_16x16x32_bf16 v[6:9], v[6:9], v[42:45], v[118:121]
	v_mfma_f32_16x16x32_bf16 v[118:121], v[14:17], v[34:37], v[10:13]
	ds_read_b64_tr_b16 v[10:11], v198 offset:0
	ds_read_b64_tr_b16 v[12:13], v198 offset:0x1000
	v_mfma_f32_16x16x32_bf16 v[114:117], v[14:17], v[18:21], v[6:9]
	ds_read_b64_tr_b16 v[14:15], v198 offset:0x2000
	ds_read_b64_tr_b16 v[16:17], v198 offset:0x3000
	s_waitcnt lgkmcnt(8)
	s_nop 0
	v_mfma_f32_16x16x32_bf16 v[6:9], v[142:145], v[58:61], v[106:109]
	v_mfma_f32_16x16x32_bf16 v[106:109], v[142:145], v[42:45], v[110:113]
	ds_read_b64_tr_b16 v[142:143], v199 offset:0
	ds_read_b64_tr_b16 v[144:145], v199 offset:0x1000
	v_mfma_f32_16x16x32_bf16 v[110:113], v[146:149], v[34:37], v[6:9]
	v_mfma_f32_16x16x32_bf16 v[106:109], v[146:149], v[18:21], v[106:109]
	ds_read_b64_tr_b16 v[146:147], v199 offset:0x2000
	ds_read_b64_tr_b16 v[148:149], v199 offset:0x3000
	s_waitcnt lgkmcnt(8)
	s_nop 0
	v_mfma_f32_16x16x32_bf16 v[6:9], v[150:153], v[58:61], v[98:101]
	s_nop 2
	v_exp_f32_e32 v98, v76
	v_exp_f32_e32 v99, v77
	v_mfma_f32_16x16x32_bf16 v[74:77], v[150:153], v[42:45], v[102:105]
	v_exp_f32_e32 v100, v86
	v_exp_f32_e32 v101, v87
	ds_read_b64_tr_b16 v[86:87], v200 offset:0
	v_mfma_f32_16x16x32_bf16 v[6:9], v[2:5], v[34:37], v[6:9]
	v_exp_f32_e32 v102, v88
	v_exp_f32_e32 v103, v89
	ds_read_b64_tr_b16 v[88:89], v200 offset:0x1000
	v_mfma_f32_16x16x32_bf16 v[2:5], v[2:5], v[18:21], v[74:77]
	ds_read_b64_tr_b16 v[74:75], v200 offset:0x2000
	ds_read_b64_tr_b16 v[76:77], v200 offset:0x3000
	s_waitcnt lgkmcnt(8)
	v_exp_f32_e32 v104, v22
	v_mfma_f32_16x16x32_bf16 v[78:81], v[10:13], v[58:61], v[78:81]
	v_exp_f32_e32 v105, v23
	v_exp_f32_e32 v150, v24
	v_mfma_f32_16x16x32_bf16 v[82:85], v[10:13], v[42:45], v[82:85]
	v_mfma_f32_16x16x32_bf16 v[10:13], v[14:17], v[34:37], v[78:81]
	ds_read_b64_tr_b16 v[78:79], v201 offset:0
	ds_read_b64_tr_b16 v[80:81], v201 offset:0x1000
	v_mfma_f32_16x16x32_bf16 v[14:17], v[14:17], v[18:21], v[82:85]
	ds_read_b64_tr_b16 v[82:83], v201 offset:0x2000
	ds_read_b64_tr_b16 v[84:85], v201 offset:0x3000
	s_waitcnt lgkmcnt(8)
	s_waitcnt lgkmcnt(4)
	s_nop 0
	v_mfma_f32_16x16x32_bf16 v[66:69], v[142:145], v[58:61], v[66:69]
	s_waitcnt lgkmcnt(0)
	v_mfma_f32_16x16x32_bf16 v[54:57], v[86:89], v[58:61], v[54:57]
	v_mfma_f32_16x16x32_bf16 v[58:61], v[78:81], v[58:61], v[30:33]
	v_mfma_f32_16x16x32_bf16 v[70:73], v[142:145], v[42:45], v[70:73]
	v_exp_f32_e32 v142, v25
	v_exp_f32_e32 v143, v26
	v_exp_f32_e32 v144, v27
	v_mfma_f32_16x16x32_bf16 v[22:25], v[146:149], v[34:37], v[66:69]
	v_cvt_pk_bf16_f32 v30, v90, v91
	v_cvt_pk_bf16_f32 v31, v92, v93
	v_cvt_pk_bf16_f32 v32, v94, v95
	v_exp_f32_e32 v66, v28
	v_exp_f32_e32 v67, v29
	v_mfma_f32_16x16x32_bf16 v[50:53], v[86:89], v[42:45], v[50:53]
	v_exp_f32_e32 v68, v64
	v_exp_f32_e32 v69, v65
	v_cvt_pk_bf16_f32 v33, v96, v97
	v_mfma_f32_16x16x32_bf16 v[54:57], v[74:77], v[34:37], v[54:57]
	v_cvt_pk_bf16_f32 v41, v68, v69
	v_mfma_f32_16x16x32_bf16 v[42:45], v[78:81], v[42:45], v[46:49]
	v_mfma_f32_16x16x32_bf16 v[46:49], v[82:85], v[34:37], v[58:61]
	v_cvt_pk_bf16_f32 v34, v154, v161
	v_cvt_pk_bf16_f32 v35, v98, v99
	v_cvt_pk_bf16_f32 v36, v100, v101
	v_cvt_pk_bf16_f32 v37, v102, v103
	v_mfma_f32_16x16x32_bf16 v[62:65], v[74:77], v[18:21], v[50:53]
	v_lshlrev_b32_e32 v154, 1, v156
	v_mfma_f32_16x16x32_bf16 v[58:61], v[138:141], v[34:37], v[134:137]
	s_nop 0
	v_cvt_pk_bf16_f32 v50, v104, v105
	v_cvt_pk_bf16_f32 v51, v150, v142
	v_cvt_pk_bf16_f32 v52, v143, v144
	v_cvt_pk_bf16_f32 v53, v66, v67
	v_mfma_f32_16x16x32_bf16 v[58:61], v[138:141], v[30:33], v[58:61]
	s_nop 0
	v_mfma_f32_16x16x32_bf16 v[78:81], v[138:141], v[50:53], v[130:133]
	v_mfma_f32_16x16x32_bf16 v[78:81], v[138:141], v[38:41], v[78:81]
	s_nop 4
	v_div_scale_f32 v59, s[2:3], v58, v58, 1.0
	v_mfma_f32_16x16x32_bf16 v[26:29], v[146:149], v[18:21], v[70:73]
	v_mfma_f32_16x16x32_bf16 v[18:21], v[82:85], v[18:21], v[42:45]
	v_rcp_f32_e32 v79, v59
	ds_read_b64_tr_b16 v[42:43], v202 offset:0
	ds_read_b64_tr_b16 v[44:45], v202 offset:0x1000
	ds_read_b64_tr_b16 v[66:67], v202 offset:0x2000
	ds_read_b64_tr_b16 v[68:69], v202 offset:0x3000
	ds_read_b64_tr_b16 v[70:71], v203 offset:0
	ds_read_b64_tr_b16 v[72:73], v203 offset:0x1000
	ds_read_b64_tr_b16 v[74:75], v203 offset:0x2000
	ds_read_b64_tr_b16 v[76:77], v203 offset:0x3000
	ds_read_b64_tr_b16 v[82:83], v204 offset:0
	ds_read_b64_tr_b16 v[84:85], v204 offset:0x1000
	ds_read_b64_tr_b16 v[86:87], v204 offset:0x2000
	ds_read_b64_tr_b16 v[88:89], v204 offset:0x3000
	s_nop 0
	s_waitcnt lgkmcnt(8)
; #define AT_TR4(slot, d) do { const unsigned _a = vaddr + (unsigned)vo[d]; AT_TR(r[slot][0], _a, 0); AT_TR(r[slot][1], _a, 16 * 256); AT_TR(r[slot][2], _a, 32 * 256); AT_TR(r[slot][3], _a, 48 * 256); } while (0)
; #define AT_TR4(slot, d) do { const unsigned _a = vaddr + (unsigned)vo[d]; AT_TR(r[slot][0], _a, 0); AT_TR(r[slot][1], _a, 16 * 256); AT_TR(r[slot][2], _a, 32 * 256); AT_TR(r[slot][3], _a, 48 * 256); } while (0)
; __device__ __forceinline__ void attn_pv(unsigned vaddr, const int (&vo)[8], const bf16x8 (&pf)[2][2], f32x4 (&o)[2][8], f32x4 (&ol)[2]) {
;     s16x4 r[3][4];
;     ...
;     AT_TR4(0, 0); AT_TR4(1, 1);
;     { const bf16x8 ones = (bf16x8){0x3f80, 0x3f80, 0x3f80, 0x3f80, 0x3f80, 0x3f80, 0x3f80, 0x3f80};
; #pragma unroll
;       for (int c = 0; c < 2; ++c)
; #pragma unroll
;           for (int si = 0; si < 2; ++si) ol[c] = __builtin_amdgcn_mfma_f32_16x16x32_bf16(ones, pf[c][si], ol[c], 0, 0, 0); }
; #pragma unroll
;     for (int dt = 0; dt < 8; ++dt) {
;         const int cb = dt % 3;
;         if (dt < 6) { AT_TR4((dt + 2) % 3, dt + 2); asm volatile("s_waitcnt lgkmcnt(8)" : "+v"(r[cb][0]), "+v"(r[cb][1]), "+v"(r[cb][2]), "+v"(r[cb][3])); }
;         else if (dt == 6) asm volatile("s_waitcnt lgkmcnt(4)" : "+v"(r[cb][0]), "+v"(r[cb][1]), "+v"(r[cb][2]), "+v"(r[cb][3]));
;         else asm volatile("s_waitcnt lgkmcnt(0)" : "+v"(r[cb][0]), "+v"(r[cb][1]), "+v"(r[cb][2]), "+v"(r[cb][3]));
; #pragma unroll
;         for (int si = 0; si < 2; ++si) {
;             const s16x4 lo = r[cb][2 * si], hi = r[cb][2 * si + 1];
;             const bf16x8 vf = (bf16x8){lo[0], lo[1], lo[2], lo[3], hi[0], hi[1], hi[2], hi[3]};
;             o[0][dt] = __builtin_amdgcn_mfma_f32_16x16x32_bf16(vf, pf[0][si], o[0][dt], 0, 0, 0);
;             o[1][dt] = __builtin_amdgcn_mfma_f32_16x16x32_bf16(vf, pf[1][si], o[1][dt], 0, 0, 0);
;         }
;     }
;     ...
; }
; __device__ __forceinline__ void attn_unit(LAS unsigned char* lds, int seq, int h, int qb, bf16_t* UQ, const bf16_t* KB, const bf16_t* VB, const float* rel_bias, const float* subln, float lam, float bmax) {
;     ...
;     const float i0 = 1.0f / ol[0][0], i1 = lam / ol[1][0];
;     float ss = 0.f;
; #pragma unroll
;     for (int dt = 0; dt < 8; ++dt)
; #pragma unroll
;         for (int j = 0; j < 4; ++j) { const float v = o[0][dt][j] * i0 - o[1][dt][j] * i1; o[0][dt][j] = v; ss += v * v; }
	ds_read_b64_tr_b16 v[90:91], v205 offset:0
	ds_read_b64_tr_b16 v[92:93], v205 offset:0x1000
	ds_read_b64_tr_b16 v[98:99], v205 offset:0x2000
	ds_read_b64_tr_b16 v[100:101], v205 offset:0x3000
	s_waitcnt lgkmcnt(8)
	s_nop 0
	v_mfma_f32_16x16x32_bf16 v[94:97], v[42:45], v[34:37], v[122:125]
	v_fma_f32 v60, -v59, v79, 1.0
	ds_read_b64_tr_b16 v[102:103], v206 offset:0
	ds_read_b64_tr_b16 v[104:105], v206 offset:0x1000
	v_mfma_f32_16x16x32_bf16 v[42:45], v[42:45], v[50:53], v[126:129]
	ds_read_b64_tr_b16 v[122:123], v206 offset:0x2000
	ds_read_b64_tr_b16 v[124:125], v206 offset:0x3000
	s_waitcnt lgkmcnt(8)
	v_mfma_f32_16x16x32_bf16 v[118:121], v[70:73], v[34:37], v[118:121]
	v_fmac_f32_e32 v79, v60, v79
	v_div_scale_f32 v60, vcc, 1.0, v58, 1.0
	v_mfma_f32_16x16x32_bf16 v[70:73], v[70:73], v[50:53], v[114:117]
	v_mfma_f32_16x16x32_bf16 v[110:113], v[82:85], v[34:37], v[110:113]
	v_mfma_f32_16x16x32_bf16 v[80:83], v[82:85], v[50:53], v[106:109]
	v_mul_f32_e32 v84, v60, v79
	v_fma_f32 v61, -v59, v84, v60
	v_fmac_f32_e32 v84, v61, v79
	v_mfma_f32_16x16x32_bf16 v[94:97], v[66:69], v[30:33], v[94:97]
	v_fma_f32 v59, -v59, v84, v60
	v_div_fmas_f32 v59, v59, v79, v84
	v_mfma_f32_16x16x32_bf16 v[42:45], v[66:69], v[38:41], v[42:45]
	ds_read_b64_tr_b16 v[66:67], v207 offset:0
	ds_read_b64_tr_b16 v[68:69], v207 offset:0x1000
	ds_read_b64_tr_b16 v[126:127], v207 offset:0x2000
	ds_read_b64_tr_b16 v[128:129], v207 offset:0x3000
	s_waitcnt lgkmcnt(8)
	ds_read_b64_tr_b16 v[130:131], v208 offset:0
	ds_read_b64_tr_b16 v[132:133], v208 offset:0x1000
	ds_read_b64_tr_b16 v[114:115], v208 offset:0x2000
	ds_read_b64_tr_b16 v[116:117], v208 offset:0x3000
	v_mfma_f32_16x16x32_bf16 v[118:121], v[74:77], v[30:33], v[118:121]
	s_waitcnt lgkmcnt(8)
	ds_read_b64_tr_b16 v[134:135], v209 offset:0
	ds_read_b64_tr_b16 v[136:137], v209 offset:0x1000
	v_mfma_f32_16x16x32_bf16 v[70:73], v[74:77], v[38:41], v[70:73]
	ds_read_b64_tr_b16 v[74:75], v209 offset:0x2000
	ds_read_b64_tr_b16 v[76:77], v209 offset:0x3000
	s_waitcnt lgkmcnt(8)
	s_waitcnt lgkmcnt(4)
	v_mfma_f32_16x16x32_bf16 v[2:5], v[90:93], v[50:53], v[2:5]
	s_waitcnt lgkmcnt(0)
	v_mfma_f32_16x16x32_bf16 v[60:63], v[130:133], v[50:53], v[62:65]
	s_nop 2
	v_div_scale_f32 v65, s[2:3], v78, v78, v174
	v_rcp_f32_e32 v85, v65
	v_mfma_f32_16x16x32_bf16 v[18:21], v[134:137], v[50:53], v[18:21]
	v_div_fixup_f32 v64, v59, v58, 1.0
	v_fma_f32 v79, -v65, v85, 1.0
	v_mfma_f32_16x16x32_bf16 v[58:61], v[114:117], v[38:41], v[60:63]
	v_fmac_f32_e32 v85, v79, v85
	s_nop 1
	v_div_scale_f32 v62, vcc, v174, v78, v174
	v_mfma_f32_16x16x32_bf16 v[46:49], v[134:137], v[34:37], v[46:49]
	v_mul_f32_e32 v63, v62, v85
	v_fma_f32 v79, -v65, v63, v62
	v_fmac_f32_e32 v63, v79, v85
	v_mfma_f32_16x16x32_bf16 v[18:21], v[74:77], v[38:41], v[18:21]
	v_fma_f32 v62, -v65, v63, v62
	v_div_fmas_f32 v62, v62, v85, v63
	v_div_fixup_f32 v78, v62, v78, v174
	v_mfma_f32_16x16x32_bf16 v[46:49], v[74:77], v[30:33], v[46:49]
	v_mul_f32_e64 v42, v78, v42
	v_mul_f32_e64 v43, v78, v43
	s_nop 1
	v_pk_mul_f32 v[18:19], v[78:79], v[18:19] op_sel_hi:[0,1]
	v_pk_fma_f32 v[42:43], v[64:65], v[94:95], v[42:43] op_sel_hi:[0,1,1] neg_lo:[0,0,1] neg_hi:[0,0,1]
	v_mfma_f32_16x16x32_bf16 v[6:9], v[90:93], v[34:37], v[6:9]
	v_mul_f32_e64 v44, v78, v44
	v_mul_f32_e64 v45, v78, v45
	v_pk_fma_f32 v[46:47], v[64:65], v[46:47], v[18:19] op_sel_hi:[0,1,1] neg_lo:[0,0,1] neg_hi:[0,0,1]
	v_pk_mul_f32 v[18:19], v[78:79], v[20:21] op_sel_hi:[0,1]
	v_pk_fma_f32 v[48:49], v[64:65], v[48:49], v[18:19] op_sel_hi:[0,1,1] neg_lo:[0,0,1] neg_hi:[0,0,1]
	global_load_dwordx4 v[18:21], v[158:159], off
	v_mfma_f32_16x16x32_bf16 v[2:5], v[98:101], v[38:41], v[2:5]
	v_mul_f32_e64 v60, v78, v60
	v_mul_f32_e64 v61, v78, v61
	v_pk_fma_f32 v[44:45], v[64:65], v[96:97], v[44:45] op_sel_hi:[0,1,1] neg_lo:[0,0,1] neg_hi:[0,0,1]
	v_pk_mul_f32 v[84:85], v[42:43], v[42:43]
	v_mfma_f32_16x16x32_bf16 v[54:57], v[130:133], v[34:37], v[54:57]
	v_mul_f32_e64 v70, v78, v70
	v_mul_f32_e64 v71, v78, v71
	s_nop 0
	v_pk_mul_f32 v[4:5], v[78:79], v[4:5] op_sel_hi:[0,1]
	v_pk_fma_f32 v[70:71], v[64:65], v[118:119], v[70:71] op_sel_hi:[0,1,1] neg_lo:[0,0,1] neg_hi:[0,0,1]
	v_mfma_f32_16x16x32_bf16 v[6:9], v[98:101], v[30:33], v[6:9]
	v_mul_f32_e64 v72, v78, v72
	v_mul_f32_e64 v73, v78, v73
	v_pk_fma_f32 v[72:73], v[64:65], v[120:121], v[72:73] op_sel_hi:[0,1,1] neg_lo:[0,0,1] neg_hi:[0,0,1]
	v_pk_mul_f32 v[76:77], v[46:47], v[46:47]
	v_mfma_f32_16x16x32_bf16 v[54:57], v[114:117], v[30:33], v[54:57]
	v_mfma_f32_16x16x32_bf16 v[10:13], v[102:105], v[34:37], v[10:13]
	s_nop 1
	v_fma_f32 v94, v64, v8, -v4
	v_fma_f32 v95, v64, v9, -v5
	v_pk_mul_f32 v[8:9], v[78:79], v[2:3] op_sel_hi:[0,1]
	s_nop 1
	v_pk_fma_f32 v[56:57], v[64:65], v[56:57], v[60:61] op_sel_hi:[0,1,1] neg_lo:[0,0,1] neg_hi:[0,0,1]
	v_mfma_f32_16x16x32_bf16 v[2:5], v[66:69], v[34:37], v[22:25]
	v_mul_f32_e64 v96, v94, v94
	v_mul_f32_e64 v97, v95, v95
	v_pk_mul_f32 v[74:75], v[56:57], v[56:57]
	v_mfma_f32_16x16x32_bf16 v[106:109], v[86:89], v[30:33], v[110:113]
	v_fma_f32 v22, v64, v6, -v8
	v_fma_f32 v23, v64, v7, -v9
	v_pk_mul_f32 v[24:25], v[22:23], v[22:23]
	v_mfma_f32_16x16x32_bf16 v[60:63], v[86:89], v[38:41], v[80:83]
	v_mul_f32_e64 v88, v70, v70
	v_mul_f32_e64 v89, v71, v71
	v_pk_mul_f32 v[86:87], v[72:73], v[72:73]
	v_pk_mul_f32 v[82:83], v[44:45], v[44:45]
	v_mfma_f32_16x16x32_bf16 v[10:13], v[122:125], v[30:33], v[10:13]
	s_nop 2
	v_mul_f32_e64 v60, v78, v60
	v_mul_f32_e64 v61, v78, v61
	v_pk_fma_f32 v[60:61], v[64:65], v[106:107], v[60:61] op_sel_hi:[0,1,1] neg_lo:[0,0,1] neg_hi:[0,0,1]
	v_pk_mul_f32 v[62:63], v[78:79], v[62:63] op_sel_hi:[0,1]
; __device__ __forceinline__ unsigned cvtpk(float lo, float hi) { f32x2 v = {lo, hi}; bf16x2_t b = __builtin_convertvector(v, bf16x2_t); return __builtin_bit_cast(unsigned, b); }
; #define AT_BAR(N) asm volatile("s_waitcnt vmcnt(" #N ") lgkmcnt(0)\n\ts_barrier" ::: "memory")
; __device__ __forceinline__ void attn_unit(LAS unsigned char* lds, int seq, int h, int qb, bf16_t* UQ, const bf16_t* KB, const bf16_t* VB, const float* rel_bias, const float* subln, float lam, float bmax) {
;     ...
;     const float i0 = 1.0f / ol[0][0], i1 = lam / ol[1][0];
;     float ss = 0.f;
; #pragma unroll
;     for (int dt = 0; dt < 8; ++dt)
; #pragma unroll
;         for (int j = 0; j < 4; ++j) { const float v = o[0][dt][j] * i0 - o[1][dt][j] * i1; o[0][dt][j] = v; ss += v * v; }
;     ss += __shfl_xor(ss, 16); ss += __shfl_xor(ss, 32);
;     const float rs = __builtin_amdgcn_rsqf(ss * (1.0f / 128.0f) + EPS) * 0.8f;
;     bf16_t* op = UQ + (size_t)(row0 + q0 + 16 * w + r16) * DM + 512 + 128 * h + 4 * fq;
; #pragma unroll
;     for (int dt = 0; dt < 8; ++dt) {
;         const f32x4 gsl = *(const f32x4*)(subln + 16 * dt + 4 * fq);
;         u32x2 wv; wv.x = cvtpk(o[0][dt][0] * rs * gsl[0], o[0][dt][1] * rs * gsl[1]); wv.y = cvtpk(o[0][dt][2] * rs * gsl[2], o[0][dt][3] * rs * gsl[3]);
;         *(u32x2*)(op + 16 * dt) = wv;
;     }
;     AT_BAR(0);
	v_mfma_f32_16x16x32_bf16 v[2:5], v[126:129], v[30:33], v[2:5]
	v_add_f32_e32 v30, v84, v85
	v_add_f32_e32 v30, v82, v30
	v_add_f32_e32 v30, v83, v30
	v_add_f32_e32 v30, v30, v88
	v_mfma_f32_16x16x32_bf16 v[14:17], v[102:105], v[50:53], v[14:17]
	v_add_f32_e32 v30, v89, v30
	v_add_f32_e32 v30, v86, v30
	v_pk_mul_f32 v[92:93], v[60:61], v[60:61]
	v_add_f32_e32 v30, v87, v30
	v_pk_fma_f32 v[62:63], v[64:65], v[108:109], v[62:63] op_sel_hi:[0,1,1] neg_lo:[0,0,1] neg_hi:[0,0,1]
	v_add_f32_e32 v30, v30, v92
	v_pk_mul_f32 v[90:91], v[62:63], v[62:63]
	v_mfma_f32_16x16x32_bf16 v[14:17], v[122:125], v[38:41], v[14:17]
	v_add_f32_e32 v30, v93, v30
	v_add_f32_e32 v30, v90, v30
	v_add_f32_e32 v30, v91, v30
	v_mfma_f32_16x16x32_bf16 v[6:9], v[66:69], v[50:53], v[26:29]
	v_add_f32_e32 v24, v30, v24
	s_nop 2
	v_pk_mul_f32 v[14:15], v[78:79], v[14:15] op_sel_hi:[0,1]
	v_add_f32_e32 v24, v25, v24
	v_mfma_f32_16x16x32_bf16 v[6:9], v[126:129], v[38:41], v[6:9]
	v_fma_f32 v10, v64, v10, -v14
	v_fma_f32 v11, v64, v11, -v15
	v_add_f32_e32 v24, v96, v24
	v_pk_mul_f32 v[16:17], v[78:79], v[16:17] op_sel_hi:[0,1]
	v_pk_mul_f32 v[14:15], v[10:11], v[10:11]
	v_add_f32_e32 v24, v97, v24
	v_pk_fma_f32 v[12:13], v[64:65], v[12:13], v[16:17] op_sel_hi:[0,1,1] neg_lo:[0,0,1] neg_hi:[0,0,1]
	v_add_f32_e32 v14, v24, v14
	v_pk_mul_f32 v[16:17], v[12:13], v[12:13]
	v_pk_mul_f32 v[6:7], v[78:79], v[6:7] op_sel_hi:[0,1]
	v_add_f32_e32 v14, v15, v14
	v_pk_fma_f32 v[6:7], v[64:65], v[2:3], v[6:7] op_sel_hi:[0,1,1] neg_lo:[0,0,1] neg_hi:[0,0,1]
	v_add_f32_e32 v14, v16, v14
	v_pk_mul_f32 v[8:9], v[78:79], v[8:9] op_sel_hi:[0,1]
	v_pk_mul_f32 v[2:3], v[6:7], v[6:7]
	v_add_f32_e32 v14, v17, v14
	v_pk_fma_f32 v[8:9], v[64:65], v[4:5], v[8:9] op_sel_hi:[0,1,1] neg_lo:[0,0,1] neg_hi:[0,0,1]
	v_add_f32_e32 v2, v14, v2
	v_pk_mul_f32 v[4:5], v[8:9], v[8:9]
	v_pk_mul_f32 v[26:27], v[78:79], v[58:59] op_sel_hi:[0,1]
	v_add_f32_e32 v2, v3, v2
	v_pk_fma_f32 v[26:27], v[64:65], v[54:55], v[26:27] op_sel_hi:[0,1,1] neg_lo:[0,0,1] neg_hi:[0,0,1]
	v_add_f32_e32 v2, v4, v2
	v_pk_mul_f32 v[28:29], v[26:27], v[26:27]
	v_add_f32_e32 v2, v5, v2
	v_add_f32_e32 v2, v2, v28
	v_add_f32_e32 v2, v29, v2
	v_add_f32_e32 v2, v74, v2
	v_add_f32_e32 v2, v75, v2
	v_add_f32_e32 v2, v2, v76
	v_pk_mul_f32 v[80:81], v[48:49], v[48:49]
	v_add_f32_e32 v2, v77, v2
	v_add_f32_e32 v2, v80, v2
	v_add_f32_e32 v2, v81, v2
	ds_bpermute_b32 v3, v1, v2
	v_lshl_add_u64 v[14:15], v[162:163], 0, v[154:155]
	s_waitcnt lgkmcnt(0)
	v_add_f32_e32 v2, v2, v3
	ds_bpermute_b32 v3, v157, v2
	s_waitcnt lgkmcnt(0)
	v_add_f32_e32 v2, v2, v3
	v_fmamk_f32 v2, v2, 0x3c000000, v211
	v_rsq_f32_e32 v2, v2
	s_nop 0
	v_mul_f32_e32 v16, 0x3f4ccccd, v2
	v_pk_mul_f32 v[2:3], v[42:43], v[16:17] op_sel_hi:[1,0]
	v_pk_mul_f32 v[4:5], v[44:45], v[16:17] op_sel_hi:[1,0]
	s_waitcnt vmcnt(0)
	v_pk_mul_f32 v[2:3], v[18:19], v[2:3]
	v_pk_mul_f32 v[4:5], v[20:21], v[4:5]
	v_cvt_pk_bf16_f32 v2, v2, v3
	v_cvt_pk_bf16_f32 v3, v4, v5
	global_store_dwordx2 v[14:15], v[2:3], off offset:1024
	global_load_dwordx4 v[216:219], v[158:159], off offset:64
	global_load_dwordx4 v[220:223], v[158:159], off offset:128
	global_load_dwordx4 v[224:227], v[158:159], off offset:192
	global_load_dwordx4 v[228:231], v[158:159], off offset:256
	global_load_dwordx4 v[232:235], v[158:159], off offset:320
	global_load_dwordx4 v[236:239], v[158:159], off offset:384
	global_load_dwordx4 v[240:243], v[158:159], off offset:448
	v_pk_mul_f32 v[18:19], v[70:71], v[16:17] op_sel_hi:[1,0]
	v_pk_mul_f32 v[20:21], v[94:95], v[16:17] op_sel_hi:[1,0]
	v_pk_mul_f32 v[10:11], v[10:11], v[16:17] op_sel_hi:[1,0]
	v_pk_mul_f32 v[12:13], v[12:13], v[16:17] op_sel_hi:[1,0]
	v_pk_mul_f32 v[6:7], v[6:7], v[16:17] op_sel_hi:[1,0]
	v_pk_mul_f32 v[8:9], v[8:9], v[16:17] op_sel_hi:[1,0]
	s_waitcnt vmcnt(6)
	v_pk_mul_f32 v[2:3], v[216:217], v[18:19]
	v_pk_mul_f32 v[18:19], v[72:73], v[16:17] op_sel_hi:[1,0]
	v_cvt_pk_bf16_f32 v2, v2, v3
	v_pk_mul_f32 v[4:5], v[218:219], v[18:19]
	v_pk_mul_f32 v[18:19], v[60:61], v[16:17] op_sel_hi:[1,0]
	v_cvt_pk_bf16_f32 v3, v4, v5
	global_store_dwordx2 v[14:15], v[2:3], off offset:1056
	s_waitcnt vmcnt(6)
	v_pk_mul_f32 v[2:3], v[220:221], v[18:19]
	v_pk_mul_f32 v[18:19], v[62:63], v[16:17] op_sel_hi:[1,0]
	v_cvt_pk_bf16_f32 v2, v2, v3
	v_pk_mul_f32 v[4:5], v[222:223], v[18:19]
	v_pk_mul_f32 v[18:19], v[22:23], v[16:17] op_sel_hi:[1,0]
	v_cvt_pk_bf16_f32 v3, v4, v5
	global_store_dwordx2 v[14:15], v[2:3], off offset:1088
	s_waitcnt vmcnt(6)
	v_pk_mul_f32 v[2:3], v[224:225], v[18:19]
	v_pk_mul_f32 v[4:5], v[226:227], v[20:21]
	v_cvt_pk_bf16_f32 v2, v2, v3
	v_cvt_pk_bf16_f32 v3, v4, v5
	global_store_dwordx2 v[14:15], v[2:3], off offset:1120
	s_waitcnt vmcnt(6)
	v_pk_mul_f32 v[2:3], v[228:229], v[10:11]
	v_pk_mul_f32 v[4:5], v[230:231], v[12:13]
	v_cvt_pk_bf16_f32 v2, v2, v3
	v_cvt_pk_bf16_f32 v3, v4, v5
	global_store_dwordx2 v[14:15], v[2:3], off offset:1152
	s_waitcnt vmcnt(6)
	v_pk_mul_f32 v[2:3], v[232:233], v[6:7]
	v_pk_mul_f32 v[4:5], v[234:235], v[8:9]
	v_cvt_pk_bf16_f32 v2, v2, v3
	v_cvt_pk_bf16_f32 v3, v4, v5
	global_store_dwordx2 v[14:15], v[2:3], off offset:1184
	v_pk_mul_f32 v[6:7], v[26:27], v[16:17] op_sel_hi:[1,0]
	v_pk_mul_f32 v[8:9], v[56:57], v[16:17] op_sel_hi:[1,0]
	s_waitcnt vmcnt(6)
	v_pk_mul_f32 v[2:3], v[236:237], v[6:7]
	v_pk_mul_f32 v[4:5], v[238:239], v[8:9]
	v_cvt_pk_bf16_f32 v2, v2, v3
	v_cvt_pk_bf16_f32 v3, v4, v5
	global_store_dwordx2 v[14:15], v[2:3], off offset:1216
	v_pk_mul_f32 v[6:7], v[46:47], v[16:17] op_sel_hi:[1,0]
	v_pk_mul_f32 v[8:9], v[48:49], v[16:17] op_sel_hi:[1,0]
	s_waitcnt vmcnt(6)
	v_pk_mul_f32 v[2:3], v[6:7], v[240:241]
	v_pk_mul_f32 v[4:5], v[8:9], v[242:243]
	v_cvt_pk_bf16_f32 v2, v2, v3
	v_cvt_pk_bf16_f32 v3, v4, v5
	global_store_dwordx2 v[14:15], v[2:3], off offset:1248
	s_waitcnt vmcnt(0) lgkmcnt(0)
	s_barrier
	s_cbranch_scc1 .LBB0_520

; __device__ __forceinline__ void attn_pv(unsigned vaddr, const int (&vo)[8], const bf16x8 (&pf)[2][2], f32x4 (&o)[2][8], f32x4 (&ol)[2]) {
;     s16x4 r[3][4];
;     ...
;     AT_TR4(0, 0); AT_TR4(1, 1);
;     { const bf16x8 ones = (bf16x8){0x3f80, 0x3f80, 0x3f80, 0x3f80, 0x3f80, 0x3f80, 0x3f80, 0x3f80};
; #pragma unroll
;       for (int c = 0; c < 2; ++c)
; #pragma unroll
;           for (int si = 0; si < 2; ++si) ol[c] = __builtin_amdgcn_mfma_f32_16x16x32_bf16(ones, pf[c][si], ol[c], 0, 0, 0); }
; #pragma unroll
;     for (int dt = 0; dt < 8; ++dt) {
;         const int cb = dt % 3;
;         if (dt < 6) { AT_TR4((dt + 2) % 3, dt + 2); asm volatile("s_waitcnt lgkmcnt(8)" : "+v"(r[cb][0]), "+v"(r[cb][1]), "+v"(r[cb][2]), "+v"(r[cb][3])); }
;         else if (dt == 6) asm volatile("s_waitcnt lgkmcnt(4)" : "+v"(r[cb][0]), "+v"(r[cb][1]), "+v"(r[cb][2]), "+v"(r[cb][3]));
;         else asm volatile("s_waitcnt lgkmcnt(0)" : "+v"(r[cb][0]), "+v"(r[cb][1]), "+v"(r[cb][2]), "+v"(r[cb][3]));
; #pragma unroll
;         for (int si = 0; si < 2; ++si) {
;             const s16x4 lo = r[cb][2 * si], hi = r[cb][2 * si + 1];
;             const bf16x8 vf = (bf16x8){lo[0], lo[1], lo[2], lo[3], hi[0], hi[1], hi[2], hi[3]};
;             o[0][dt] = __builtin_amdgcn_mfma_f32_16x16x32_bf16(vf, pf[0][si], o[0][dt], 0, 0, 0);
;             o[1][dt] = __builtin_amdgcn_mfma_f32_16x16x32_bf16(vf, pf[1][si], o[1][dt], 0, 0, 0);
;         }
;     }
;     ...
; }
; template <bool QK, bool PV> ...
;     ...
;     if constexpr (PV) { AT_TR4(0, 0); AT_TR4(1, 1);
;         const bf16x8 ones = (bf16x8){0x3f80, 0x3f80, 0x3f80, 0x3f80, 0x3f80, 0x3f80, 0x3f80, 0x3f80};
; #pragma unroll
;         for (int c = 0; c < 2; ++c)
; #pragma unroll
;             for (int si = 0; si < 2; ++si) ol[c] = __builtin_amdgcn_mfma_f32_16x16x32_bf16(ones, pf[c][si], ol[c], 0, 0, 0); }
; #pragma unroll
;     for (int dt = 0; dt < 8; ++dt) {
;         if constexpr (PV) {
;             const int cb = dt % 3;
;             if (dt < 6) { AT_TR4((dt + 2) % 3, dt + 2); asm volatile("s_waitcnt lgkmcnt(8)" : "+v"(r[cb][0]), "+v"(r[cb][1]), "+v"(r[cb][2]), "+v"(r[cb][3])); }
;             else if (dt == 6) asm volatile("s_waitcnt lgkmcnt(4)" : "+v"(r[cb][0]), "+v"(r[cb][1]), "+v"(r[cb][2]), "+v"(r[cb][3]));
;             else asm volatile("s_waitcnt lgkmcnt(0)" : "+v"(r[cb][0]), "+v"(r[cb][1]), "+v"(r[cb][2]), "+v"(r[cb][3]));
; #pragma unroll
.Lat_yskip_p:
	v_mov_b64_e32 v[140:141], s[6:7]
	v_mov_b64_e32 v[138:139], s[4:5]
	ds_read_b64_tr_b16 v[2:3], v192 offset:0
	ds_read_b64_tr_b16 v[4:5], v192 offset:0x1000
	ds_read_b64_tr_b16 v[10:11], v192 offset:0x2000
	ds_read_b64_tr_b16 v[12:13], v192 offset:0x3000
	v_exp_f32_e32 v154, v74
	s_nop 0
	v_mfma_f32_16x16x32_bf16 v[6:9], v[138:141], v[58:61], v[134:137]
	v_exp_f32_e32 v164, v75
	v_exp_f32_e32 v90, v90
	v_exp_f32_e32 v91, v91
	v_mfma_f32_16x16x32_bf16 v[134:137], v[138:141], v[34:37], v[6:9]
	ds_read_b64_tr_b16 v[6:7], v193 offset:0
	ds_read_b64_tr_b16 v[8:9], v193 offset:0x1000
	ds_read_b64_tr_b16 v[14:15], v193 offset:0x2000
	ds_read_b64_tr_b16 v[16:17], v193 offset:0x3000
	ds_read_b64_tr_b16 v[142:143], v194 offset:0
	ds_read_b64_tr_b16 v[144:145], v194 offset:0x1000
	ds_read_b64_tr_b16 v[146:147], v194 offset:0x2000
	ds_read_b64_tr_b16 v[148:149], v194 offset:0x3000
	s_waitcnt lgkmcnt(8)
	ds_read_b64_tr_b16 v[150:151], v195 offset:0
	ds_read_b64_tr_b16 v[152:153], v195 offset:0x1000
	v_mfma_f32_16x16x32_bf16 v[130:133], v[138:141], v[42:45], v[130:133]
	v_exp_f32_e32 v92, v92
	v_exp_f32_e32 v93, v93
	v_exp_f32_e32 v94, v94
	v_mfma_f32_16x16x32_bf16 v[126:129], v[2:5], v[58:61], v[126:129]
	v_exp_f32_e32 v95, v95
	v_exp_f32_e32 v96, v96
	v_exp_f32_e32 v97, v97
	v_mfma_f32_16x16x32_bf16 v[2:5], v[2:5], v[42:45], v[122:125]
	v_exp_f32_e32 v38, v38
	v_exp_f32_e32 v39, v39
	v_exp_f32_e32 v40, v40
	v_mfma_f32_16x16x32_bf16 v[122:125], v[10:13], v[34:37], v[126:129]
	v_exp_f32_e32 v41, v41
	v_exp_f32_e32 v62, v62
	v_exp_f32_e32 v63, v63
	v_mfma_f32_16x16x32_bf16 v[126:129], v[10:13], v[18:21], v[2:5]
	ds_read_b64_tr_b16 v[2:3], v195 offset:0x2000
	ds_read_b64_tr_b16 v[4:5], v195 offset:0x3000
	s_waitcnt lgkmcnt(8)
	v_mfma_f32_16x16x32_bf16 v[130:133], v[138:141], v[18:21], v[130:133]
	v_cvt_pk_bf16_f32 v38, v38, v39
	v_cvt_pk_bf16_f32 v39, v40, v41
	v_cvt_pk_bf16_f32 v40, v62, v63
	v_mfma_f32_16x16x32_bf16 v[10:13], v[6:9], v[58:61], v[114:117]
	s_add_i32 s43, s43, s30
	s_add_i32 s42, s42, s30
	s_cmpk_gt_i32 s43, 0x3ff
	v_mfma_f32_16x16x32_bf16 v[6:9], v[6:9], v[42:45], v[118:121]
	v_mfma_f32_16x16x32_bf16 v[118:121], v[14:17], v[34:37], v[10:13]
	ds_read_b64_tr_b16 v[10:11], v196 offset:0
	ds_read_b64_tr_b16 v[12:13], v196 offset:0x1000
	v_mfma_f32_16x16x32_bf16 v[114:117], v[14:17], v[18:21], v[6:9]
	ds_read_b64_tr_b16 v[14:15], v196 offset:0x2000
	ds_read_b64_tr_b16 v[16:17], v196 offset:0x3000
	s_waitcnt lgkmcnt(8)
	s_nop 0
	v_mfma_f32_16x16x32_bf16 v[6:9], v[142:145], v[58:61], v[106:109]
	v_mfma_f32_16x16x32_bf16 v[106:109], v[142:145], v[42:45], v[110:113]
	ds_read_b64_tr_b16 v[142:143], v197 offset:0
	ds_read_b64_tr_b16 v[144:145], v197 offset:0x1000
	v_mfma_f32_16x16x32_bf16 v[110:113], v[146:149], v[34:37], v[6:9]
	v_mfma_f32_16x16x32_bf16 v[106:109], v[146:149], v[18:21], v[106:109]
	ds_read_b64_tr_b16 v[146:147], v197 offset:0x2000
	ds_read_b64_tr_b16 v[148:149], v197 offset:0x3000
	s_waitcnt lgkmcnt(8)
	s_nop 0
	v_mfma_f32_16x16x32_bf16 v[6:9], v[150:153], v[58:61], v[98:101]
	s_nop 2
	v_exp_f32_e32 v98, v76
	v_exp_f32_e32 v99, v77
	v_mfma_f32_16x16x32_bf16 v[74:77], v[150:153], v[42:45], v[102:105]
	v_exp_f32_e32 v100, v86
	v_exp_f32_e32 v101, v87
	ds_read_b64_tr_b16 v[86:87], v198 offset:0
	v_mfma_f32_16x16x32_bf16 v[6:9], v[2:5], v[34:37], v[6:9]
	v_exp_f32_e32 v102, v88
	v_exp_f32_e32 v103, v89
	ds_read_b64_tr_b16 v[88:89], v198 offset:0x1000
	v_mfma_f32_16x16x32_bf16 v[2:5], v[2:5], v[18:21], v[74:77]
	ds_read_b64_tr_b16 v[74:75], v198 offset:0x2000
	ds_read_b64_tr_b16 v[76:77], v198 offset:0x3000
	s_waitcnt lgkmcnt(8)
	v_exp_f32_e32 v104, v22
	v_mfma_f32_16x16x32_bf16 v[78:81], v[10:13], v[58:61], v[78:81]
	v_exp_f32_e32 v105, v23
	v_exp_f32_e32 v150, v24
	v_mfma_f32_16x16x32_bf16 v[82:85], v[10:13], v[42:45], v[82:85]
	v_mfma_f32_16x16x32_bf16 v[10:13], v[14:17], v[34:37], v[78:81]
	ds_read_b64_tr_b16 v[78:79], v199 offset:0
	ds_read_b64_tr_b16 v[80:81], v199 offset:0x1000
	v_mfma_f32_16x16x32_bf16 v[14:17], v[14:17], v[18:21], v[82:85]
	ds_read_b64_tr_b16 v[82:83], v199 offset:0x2000
	ds_read_b64_tr_b16 v[84:85], v199 offset:0x3000
	s_waitcnt lgkmcnt(8)
	s_waitcnt lgkmcnt(4)
	s_nop 0
	v_mfma_f32_16x16x32_bf16 v[66:69], v[142:145], v[58:61], v[66:69]
	s_waitcnt lgkmcnt(0)
	v_mfma_f32_16x16x32_bf16 v[54:57], v[86:89], v[58:61], v[54:57]
	v_mfma_f32_16x16x32_bf16 v[58:61], v[78:81], v[58:61], v[30:33]
	v_mfma_f32_16x16x32_bf16 v[70:73], v[142:145], v[42:45], v[70:73]
	v_exp_f32_e32 v142, v25
	v_exp_f32_e32 v143, v26
	v_exp_f32_e32 v144, v27
	v_mfma_f32_16x16x32_bf16 v[22:25], v[146:149], v[34:37], v[66:69]
	v_cvt_pk_bf16_f32 v30, v90, v91
	v_cvt_pk_bf16_f32 v31, v92, v93
	v_cvt_pk_bf16_f32 v32, v94, v95
	v_exp_f32_e32 v66, v28
	v_exp_f32_e32 v67, v29
	v_mfma_f32_16x16x32_bf16 v[50:53], v[86:89], v[42:45], v[50:53]
	v_exp_f32_e32 v68, v64
	v_exp_f32_e32 v69, v65
	v_cvt_pk_bf16_f32 v33, v96, v97
	v_mfma_f32_16x16x32_bf16 v[54:57], v[74:77], v[34:37], v[54:57]
	v_cvt_pk_bf16_f32 v41, v68, v69
	v_mfma_f32_16x16x32_bf16 v[42:45], v[78:81], v[42:45], v[46:49]
	v_mfma_f32_16x16x32_bf16 v[46:49], v[82:85], v[34:37], v[58:61]
	v_cvt_pk_bf16_f32 v34, v154, v164
	v_cvt_pk_bf16_f32 v35, v98, v99
	v_cvt_pk_bf16_f32 v36, v100, v101
	v_cvt_pk_bf16_f32 v37, v102, v103
	v_mfma_f32_16x16x32_bf16 v[62:65], v[74:77], v[18:21], v[50:53]
	v_lshlrev_b32_e32 v154, 1, v156
	v_mfma_f32_16x16x32_bf16 v[58:61], v[138:141], v[34:37], v[134:137]
	s_nop 0
	v_cvt_pk_bf16_f32 v50, v104, v105
	v_cvt_pk_bf16_f32 v51, v150, v142
	v_cvt_pk_bf16_f32 v52, v143, v144
	v_cvt_pk_bf16_f32 v53, v66, v67
	v_mfma_f32_16x16x32_bf16 v[58:61], v[138:141], v[30:33], v[58:61]
	s_nop 0
	v_mfma_f32_16x16x32_bf16 v[78:81], v[138:141], v[50:53], v[130:133]
	v_mfma_f32_16x16x32_bf16 v[78:81], v[138:141], v[38:41], v[78:81]
	s_nop 4
	v_div_scale_f32 v59, s[2:3], v58, v58, 1.0
	v_mfma_f32_16x16x32_bf16 v[26:29], v[146:149], v[18:21], v[70:73]
	v_mfma_f32_16x16x32_bf16 v[18:21], v[82:85], v[18:21], v[42:45]
	v_rcp_f32_e32 v79, v59
	ds_read_b64_tr_b16 v[42:43], v200 offset:0
	ds_read_b64_tr_b16 v[44:45], v200 offset:0x1000
	ds_read_b64_tr_b16 v[66:67], v200 offset:0x2000
	ds_read_b64_tr_b16 v[68:69], v200 offset:0x3000
	ds_read_b64_tr_b16 v[70:71], v201 offset:0
	ds_read_b64_tr_b16 v[72:73], v201 offset:0x1000
	ds_read_b64_tr_b16 v[74:75], v201 offset:0x2000
	ds_read_b64_tr_b16 v[76:77], v201 offset:0x3000
	ds_read_b64_tr_b16 v[82:83], v202 offset:0
	ds_read_b64_tr_b16 v[84:85], v202 offset:0x1000
	ds_read_b64_tr_b16 v[86:87], v202 offset:0x2000
	ds_read_b64_tr_b16 v[88:89], v202 offset:0x3000
	s_nop 0
	s_waitcnt lgkmcnt(8)
; #define AT_TR4(slot, d) do { const unsigned _a = vaddr + (unsigned)vo[d]; AT_TR(r[slot][0], _a, 0); AT_TR(r[slot][1], _a, 16 * 256); AT_TR(r[slot][2], _a, 32 * 256); AT_TR(r[slot][3], _a, 48 * 256); } while (0)
; #define AT_TR4(slot, d) do { const unsigned _a = vaddr + (unsigned)vo[d]; AT_TR(r[slot][0], _a, 0); AT_TR(r[slot][1], _a, 16 * 256); AT_TR(r[slot][2], _a, 32 * 256); AT_TR(r[slot][3], _a, 48 * 256); } while (0)
; __device__ __forceinline__ void attn_pv(unsigned vaddr, const int (&vo)[8], const bf16x8 (&pf)[2][2], f32x4 (&o)[2][8], f32x4 (&ol)[2]) {
;     s16x4 r[3][4];
;     ...
;     AT_TR4(0, 0); AT_TR4(1, 1);
;     { const bf16x8 ones = (bf16x8){0x3f80, 0x3f80, 0x3f80, 0x3f80, 0x3f80, 0x3f80, 0x3f80, 0x3f80};
; #pragma unroll
;       for (int c = 0; c < 2; ++c)
; #pragma unroll
;           for (int si = 0; si < 2; ++si) ol[c] = __builtin_amdgcn_mfma_f32_16x16x32_bf16(ones, pf[c][si], ol[c], 0, 0, 0); }
; #pragma unroll
;     for (int dt = 0; dt < 8; ++dt) {
;         const int cb = dt % 3;
;         if (dt < 6) { AT_TR4((dt + 2) % 3, dt + 2); asm volatile("s_waitcnt lgkmcnt(8)" : "+v"(r[cb][0]), "+v"(r[cb][1]), "+v"(r[cb][2]), "+v"(r[cb][3])); }
;         else if (dt == 6) asm volatile("s_waitcnt lgkmcnt(4)" : "+v"(r[cb][0]), "+v"(r[cb][1]), "+v"(r[cb][2]), "+v"(r[cb][3]));
;         else asm volatile("s_waitcnt lgkmcnt(0)" : "+v"(r[cb][0]), "+v"(r[cb][1]), "+v"(r[cb][2]), "+v"(r[cb][3]));
; #pragma unroll
;         for (int si = 0; si < 2; ++si) {
;             const s16x4 lo = r[cb][2 * si], hi = r[cb][2 * si + 1];
;             const bf16x8 vf = (bf16x8){lo[0], lo[1], lo[2], lo[3], hi[0], hi[1], hi[2], hi[3]};
;             o[0][dt] = __builtin_amdgcn_mfma_f32_16x16x32_bf16(vf, pf[0][si], o[0][dt], 0, 0, 0);
;             o[1][dt] = __builtin_amdgcn_mfma_f32_16x16x32_bf16(vf, pf[1][si], o[1][dt], 0, 0, 0);
;         }
;     }
;     ...
; }
; __device__ __forceinline__ void attn_unit(LAS unsigned char* lds, int seq, int h, int qb, bf16_t* UQ, const bf16_t* KB, const bf16_t* VB, const float* rel_bias, const float* subln, float lam, float bmax) {
;     ...
;     const float i0 = 1.0f / ol[0][0], i1 = lam / ol[1][0];
;     float ss = 0.f;
; #pragma unroll
;     for (int dt = 0; dt < 8; ++dt)
; #pragma unroll
;         for (int j = 0; j < 4; ++j) { const float v = o[0][dt][j] * i0 - o[1][dt][j] * i1; o[0][dt][j] = v; ss += v * v; }
	ds_read_b64_tr_b16 v[90:91], v203 offset:0
	ds_read_b64_tr_b16 v[92:93], v203 offset:0x1000
	ds_read_b64_tr_b16 v[98:99], v203 offset:0x2000
	ds_read_b64_tr_b16 v[100:101], v203 offset:0x3000
	s_waitcnt lgkmcnt(8)
	s_nop 0
	v_mfma_f32_16x16x32_bf16 v[94:97], v[42:45], v[34:37], v[122:125]
	v_fma_f32 v60, -v59, v79, 1.0
	ds_read_b64_tr_b16 v[102:103], v204 offset:0
	ds_read_b64_tr_b16 v[104:105], v204 offset:0x1000
	v_mfma_f32_16x16x32_bf16 v[42:45], v[42:45], v[50:53], v[126:129]
	ds_read_b64_tr_b16 v[122:123], v204 offset:0x2000
	ds_read_b64_tr_b16 v[124:125], v204 offset:0x3000
	s_waitcnt lgkmcnt(8)
	v_mfma_f32_16x16x32_bf16 v[118:121], v[70:73], v[34:37], v[118:121]
	v_fmac_f32_e32 v79, v60, v79
	v_div_scale_f32 v60, vcc, 1.0, v58, 1.0
	v_mfma_f32_16x16x32_bf16 v[70:73], v[70:73], v[50:53], v[114:117]
	v_mfma_f32_16x16x32_bf16 v[110:113], v[82:85], v[34:37], v[110:113]
	v_mfma_f32_16x16x32_bf16 v[80:83], v[82:85], v[50:53], v[106:109]
	v_mul_f32_e32 v84, v60, v79
	v_fma_f32 v61, -v59, v84, v60
	v_fmac_f32_e32 v84, v61, v79
	v_mfma_f32_16x16x32_bf16 v[94:97], v[66:69], v[30:33], v[94:97]
	v_fma_f32 v59, -v59, v84, v60
	v_div_fmas_f32 v59, v59, v79, v84
	v_mfma_f32_16x16x32_bf16 v[42:45], v[66:69], v[38:41], v[42:45]
	ds_read_b64_tr_b16 v[66:67], v205 offset:0
	ds_read_b64_tr_b16 v[68:69], v205 offset:0x1000
	ds_read_b64_tr_b16 v[126:127], v205 offset:0x2000
	ds_read_b64_tr_b16 v[128:129], v205 offset:0x3000
	s_waitcnt lgkmcnt(8)
	ds_read_b64_tr_b16 v[130:131], v206 offset:0
	ds_read_b64_tr_b16 v[132:133], v206 offset:0x1000
	ds_read_b64_tr_b16 v[114:115], v206 offset:0x2000
	ds_read_b64_tr_b16 v[116:117], v206 offset:0x3000
	v_mfma_f32_16x16x32_bf16 v[118:121], v[74:77], v[30:33], v[118:121]
	s_waitcnt lgkmcnt(8)
	ds_read_b64_tr_b16 v[134:135], v207 offset:0
	ds_read_b64_tr_b16 v[136:137], v207 offset:0x1000
	v_mfma_f32_16x16x32_bf16 v[70:73], v[74:77], v[38:41], v[70:73]
	ds_read_b64_tr_b16 v[74:75], v207 offset:0x2000
	ds_read_b64_tr_b16 v[76:77], v207 offset:0x3000
	s_waitcnt lgkmcnt(8)
	s_waitcnt lgkmcnt(4)
	v_mfma_f32_16x16x32_bf16 v[2:5], v[90:93], v[50:53], v[2:5]
	s_waitcnt lgkmcnt(0)
	v_mfma_f32_16x16x32_bf16 v[60:63], v[130:133], v[50:53], v[62:65]
	s_nop 2
	v_div_scale_f32 v65, s[2:3], v78, v78, v174
	v_rcp_f32_e32 v85, v65
	v_mfma_f32_16x16x32_bf16 v[18:21], v[134:137], v[50:53], v[18:21]
	v_div_fixup_f32 v64, v59, v58, 1.0
	v_fma_f32 v79, -v65, v85, 1.0
	v_mfma_f32_16x16x32_bf16 v[58:61], v[114:117], v[38:41], v[60:63]
	v_fmac_f32_e32 v85, v79, v85
	s_nop 1
	v_div_scale_f32 v62, vcc, v174, v78, v174
	v_mfma_f32_16x16x32_bf16 v[46:49], v[134:137], v[34:37], v[46:49]
	v_mul_f32_e32 v63, v62, v85
	v_fma_f32 v79, -v65, v63, v62
	v_fmac_f32_e32 v63, v79, v85
	v_mfma_f32_16x16x32_bf16 v[18:21], v[74:77], v[38:41], v[18:21]
	v_fma_f32 v62, -v65, v63, v62
	v_div_fmas_f32 v62, v62, v85, v63
	v_div_fixup_f32 v78, v62, v78, v174
	v_mfma_f32_16x16x32_bf16 v[46:49], v[74:77], v[30:33], v[46:49]
	v_mul_f32_e64 v42, v78, v42
	v_mul_f32_e64 v43, v78, v43
	s_nop 1
	v_pk_mul_f32 v[18:19], v[78:79], v[18:19] op_sel_hi:[0,1]
	v_pk_fma_f32 v[42:43], v[64:65], v[94:95], v[42:43] op_sel_hi:[0,1,1] neg_lo:[0,0,1] neg_hi:[0,0,1]
	v_mfma_f32_16x16x32_bf16 v[6:9], v[90:93], v[34:37], v[6:9]
	v_mul_f32_e64 v44, v78, v44
	v_mul_f32_e64 v45, v78, v45
	v_pk_fma_f32 v[46:47], v[64:65], v[46:47], v[18:19] op_sel_hi:[0,1,1] neg_lo:[0,0,1] neg_hi:[0,0,1]
	v_pk_mul_f32 v[18:19], v[78:79], v[20:21] op_sel_hi:[0,1]
	v_pk_fma_f32 v[48:49], v[64:65], v[48:49], v[18:19] op_sel_hi:[0,1,1] neg_lo:[0,0,1] neg_hi:[0,0,1]
	global_load_dwordx4 v[18:21], v[158:159], off
	v_mfma_f32_16x16x32_bf16 v[2:5], v[98:101], v[38:41], v[2:5]
	v_mul_f32_e64 v60, v78, v60
	v_mul_f32_e64 v61, v78, v61
	v_pk_fma_f32 v[44:45], v[64:65], v[96:97], v[44:45] op_sel_hi:[0,1,1] neg_lo:[0,0,1] neg_hi:[0,0,1]
	v_pk_mul_f32 v[84:85], v[42:43], v[42:43]
	v_mfma_f32_16x16x32_bf16 v[54:57], v[130:133], v[34:37], v[54:57]
	v_mul_f32_e64 v70, v78, v70
	v_mul_f32_e64 v71, v78, v71
	s_nop 0
	v_pk_mul_f32 v[4:5], v[78:79], v[4:5] op_sel_hi:[0,1]
	v_pk_fma_f32 v[70:71], v[64:65], v[118:119], v[70:71] op_sel_hi:[0,1,1] neg_lo:[0,0,1] neg_hi:[0,0,1]
	v_mfma_f32_16x16x32_bf16 v[6:9], v[98:101], v[30:33], v[6:9]
	v_mul_f32_e64 v72, v78, v72
	v_mul_f32_e64 v73, v78, v73
	v_pk_fma_f32 v[72:73], v[64:65], v[120:121], v[72:73] op_sel_hi:[0,1,1] neg_lo:[0,0,1] neg_hi:[0,0,1]
	v_pk_mul_f32 v[76:77], v[46:47], v[46:47]
	v_mfma_f32_16x16x32_bf16 v[54:57], v[114:117], v[30:33], v[54:57]
	v_mfma_f32_16x16x32_bf16 v[10:13], v[102:105], v[34:37], v[10:13]
	s_nop 1
	v_fma_f32 v94, v64, v8, -v4
	v_fma_f32 v95, v64, v9, -v5
	v_pk_mul_f32 v[8:9], v[78:79], v[2:3] op_sel_hi:[0,1]
	s_nop 1
	v_pk_fma_f32 v[56:57], v[64:65], v[56:57], v[60:61] op_sel_hi:[0,1,1] neg_lo:[0,0,1] neg_hi:[0,0,1]
	v_mfma_f32_16x16x32_bf16 v[2:5], v[66:69], v[34:37], v[22:25]
	v_mul_f32_e64 v96, v94, v94
	v_mul_f32_e64 v97, v95, v95
	v_pk_mul_f32 v[74:75], v[56:57], v[56:57]
	v_mfma_f32_16x16x32_bf16 v[106:109], v[86:89], v[30:33], v[110:113]
	v_fma_f32 v22, v64, v6, -v8
	v_fma_f32 v23, v64, v7, -v9
	v_pk_mul_f32 v[24:25], v[22:23], v[22:23]
	v_mfma_f32_16x16x32_bf16 v[60:63], v[86:89], v[38:41], v[80:83]
	v_mul_f32_e64 v88, v70, v70
	v_mul_f32_e64 v89, v71, v71
	v_pk_mul_f32 v[86:87], v[72:73], v[72:73]
	v_pk_mul_f32 v[82:83], v[44:45], v[44:45]
	v_mfma_f32_16x16x32_bf16 v[10:13], v[122:125], v[30:33], v[10:13]
	s_nop 2
	v_mul_f32_e64 v60, v78, v60
	v_mul_f32_e64 v61, v78, v61
	v_pk_fma_f32 v[60:61], v[64:65], v[106:107], v[60:61] op_sel_hi:[0,1,1] neg_lo:[0,0,1] neg_hi:[0,0,1]
	v_pk_mul_f32 v[62:63], v[78:79], v[62:63] op_sel_hi:[0,1]
; __device__ __forceinline__ unsigned cvtpk(float lo, float hi) { f32x2 v = {lo, hi}; bf16x2_t b = __builtin_convertvector(v, bf16x2_t); return __builtin_bit_cast(unsigned, b); }
; #define AT_BAR(N) asm volatile("s_waitcnt vmcnt(" #N ") lgkmcnt(0)\n\ts_barrier" ::: "memory")
; __device__ __forceinline__ void attn_unit(LAS unsigned char* lds, int seq, int h, int qb, bf16_t* UQ, const bf16_t* KB, const bf16_t* VB, const float* rel_bias, const float* subln, float lam, float bmax) {
;     ...
;     const float i0 = 1.0f / ol[0][0], i1 = lam / ol[1][0];
;     float ss = 0.f;
; #pragma unroll
;     for (int dt = 0; dt < 8; ++dt)
; #pragma unroll
;         for (int j = 0; j < 4; ++j) { const float v = o[0][dt][j] * i0 - o[1][dt][j] * i1; o[0][dt][j] = v; ss += v * v; }
;     ss += __shfl_xor(ss, 16); ss += __shfl_xor(ss, 32);
;     const float rs = __builtin_amdgcn_rsqf(ss * (1.0f / 128.0f) + EPS) * 0.8f;
;     bf16_t* op = UQ + (size_t)(row0 + q0 + 16 * w + r16) * DM + 512 + 128 * h + 4 * fq;
; #pragma unroll
;     for (int dt = 0; dt < 8; ++dt) {
;         const f32x4 gsl = *(const f32x4*)(subln + 16 * dt + 4 * fq);
;         u32x2 wv; wv.x = cvtpk(o[0][dt][0] * rs * gsl[0], o[0][dt][1] * rs * gsl[1]); wv.y = cvtpk(o[0][dt][2] * rs * gsl[2], o[0][dt][3] * rs * gsl[3]);
;         *(u32x2*)(op + 16 * dt) = wv;
;     }
;     AT_BAR(0);
	v_mfma_f32_16x16x32_bf16 v[2:5], v[126:129], v[30:33], v[2:5]
	v_add_f32_e32 v30, v84, v85
	v_add_f32_e32 v30, v82, v30
	v_add_f32_e32 v30, v83, v30
	v_add_f32_e32 v30, v30, v88
	v_mfma_f32_16x16x32_bf16 v[14:17], v[102:105], v[50:53], v[14:17]
	v_add_f32_e32 v30, v89, v30
	v_add_f32_e32 v30, v86, v30
	v_pk_mul_f32 v[92:93], v[60:61], v[60:61]
	v_add_f32_e32 v30, v87, v30
	v_pk_fma_f32 v[62:63], v[64:65], v[108:109], v[62:63] op_sel_hi:[0,1,1] neg_lo:[0,0,1] neg_hi:[0,0,1]
	v_add_f32_e32 v30, v30, v92
	v_pk_mul_f32 v[90:91], v[62:63], v[62:63]
	v_mfma_f32_16x16x32_bf16 v[14:17], v[122:125], v[38:41], v[14:17]
	v_add_f32_e32 v30, v93, v30
	v_add_f32_e32 v30, v90, v30
	v_add_f32_e32 v30, v91, v30
	v_mfma_f32_16x16x32_bf16 v[6:9], v[66:69], v[50:53], v[26:29]
	v_add_f32_e32 v24, v30, v24
	s_nop 2
	v_pk_mul_f32 v[14:15], v[78:79], v[14:15] op_sel_hi:[0,1]
	v_add_f32_e32 v24, v25, v24
	v_mfma_f32_16x16x32_bf16 v[6:9], v[126:129], v[38:41], v[6:9]
	v_fma_f32 v10, v64, v10, -v14
	v_fma_f32 v11, v64, v11, -v15
	v_add_f32_e32 v24, v96, v24
	v_pk_mul_f32 v[16:17], v[78:79], v[16:17] op_sel_hi:[0,1]
	v_pk_mul_f32 v[14:15], v[10:11], v[10:11]
	v_add_f32_e32 v24, v97, v24
	v_pk_fma_f32 v[12:13], v[64:65], v[12:13], v[16:17] op_sel_hi:[0,1,1] neg_lo:[0,0,1] neg_hi:[0,0,1]
	v_add_f32_e32 v14, v24, v14
	v_pk_mul_f32 v[16:17], v[12:13], v[12:13]
	v_pk_mul_f32 v[6:7], v[78:79], v[6:7] op_sel_hi:[0,1]
	v_add_f32_e32 v14, v15, v14
	v_pk_fma_f32 v[6:7], v[64:65], v[2:3], v[6:7] op_sel_hi:[0,1,1] neg_lo:[0,0,1] neg_hi:[0,0,1]
	v_add_f32_e32 v14, v16, v14
	v_pk_mul_f32 v[8:9], v[78:79], v[8:9] op_sel_hi:[0,1]
	v_pk_mul_f32 v[2:3], v[6:7], v[6:7]
	v_add_f32_e32 v14, v17, v14
	v_pk_fma_f32 v[8:9], v[64:65], v[4:5], v[8:9] op_sel_hi:[0,1,1] neg_lo:[0,0,1] neg_hi:[0,0,1]
	v_add_f32_e32 v2, v14, v2
	v_pk_mul_f32 v[4:5], v[8:9], v[8:9]
	v_pk_mul_f32 v[26:27], v[78:79], v[58:59] op_sel_hi:[0,1]
	v_add_f32_e32 v2, v3, v2
	v_pk_fma_f32 v[26:27], v[64:65], v[54:55], v[26:27] op_sel_hi:[0,1,1] neg_lo:[0,0,1] neg_hi:[0,0,1]
	v_add_f32_e32 v2, v4, v2
	v_pk_mul_f32 v[28:29], v[26:27], v[26:27]
	v_add_f32_e32 v2, v5, v2
	v_add_f32_e32 v2, v2, v28
	v_add_f32_e32 v2, v29, v2
	v_add_f32_e32 v2, v74, v2
	v_add_f32_e32 v2, v75, v2
	v_add_f32_e32 v2, v2, v76
	v_pk_mul_f32 v[80:81], v[48:49], v[48:49]
	v_add_f32_e32 v2, v77, v2
	v_add_f32_e32 v2, v80, v2
	v_add_f32_e32 v2, v81, v2
	ds_bpermute_b32 v3, v1, v2
	v_lshl_add_u64 v[14:15], v[162:163], 0, v[154:155]
	s_waitcnt lgkmcnt(0)
	v_add_f32_e32 v2, v2, v3
	ds_bpermute_b32 v3, v157, v2
	s_waitcnt lgkmcnt(0)
	v_add_f32_e32 v2, v2, v3
	v_fmamk_f32 v2, v2, 0x3c000000, v209
	v_rsq_f32_e32 v2, v2
	s_nop 0
	v_mul_f32_e32 v16, 0x3f4ccccd, v2
	v_pk_mul_f32 v[2:3], v[42:43], v[16:17] op_sel_hi:[1,0]
	v_pk_mul_f32 v[4:5], v[44:45], v[16:17] op_sel_hi:[1,0]
	s_waitcnt vmcnt(0)
	v_pk_mul_f32 v[2:3], v[18:19], v[2:3]
	v_pk_mul_f32 v[4:5], v[20:21], v[4:5]
	v_cvt_pk_bf16_f32 v2, v2, v3
	v_cvt_pk_bf16_f32 v3, v4, v5
	global_store_dwordx2 v[14:15], v[2:3], off offset:1024
	global_load_dwordx4 v[216:219], v[158:159], off offset:64
	global_load_dwordx4 v[220:223], v[158:159], off offset:128
	global_load_dwordx4 v[224:227], v[158:159], off offset:192
	global_load_dwordx4 v[228:231], v[158:159], off offset:256
	global_load_dwordx4 v[232:235], v[158:159], off offset:320
	global_load_dwordx4 v[236:239], v[158:159], off offset:384
	global_load_dwordx4 v[240:243], v[158:159], off offset:448
	v_pk_mul_f32 v[18:19], v[70:71], v[16:17] op_sel_hi:[1,0]
	v_pk_mul_f32 v[20:21], v[94:95], v[16:17] op_sel_hi:[1,0]
	v_pk_mul_f32 v[10:11], v[10:11], v[16:17] op_sel_hi:[1,0]
	v_pk_mul_f32 v[12:13], v[12:13], v[16:17] op_sel_hi:[1,0]
	v_pk_mul_f32 v[6:7], v[6:7], v[16:17] op_sel_hi:[1,0]
	v_pk_mul_f32 v[8:9], v[8:9], v[16:17] op_sel_hi:[1,0]
	s_waitcnt vmcnt(6)
	v_pk_mul_f32 v[2:3], v[216:217], v[18:19]
	v_pk_mul_f32 v[18:19], v[72:73], v[16:17] op_sel_hi:[1,0]
	v_cvt_pk_bf16_f32 v2, v2, v3
	v_pk_mul_f32 v[4:5], v[218:219], v[18:19]
	v_pk_mul_f32 v[18:19], v[60:61], v[16:17] op_sel_hi:[1,0]
	v_cvt_pk_bf16_f32 v3, v4, v5
	global_store_dwordx2 v[14:15], v[2:3], off offset:1056
	s_waitcnt vmcnt(6)
	v_pk_mul_f32 v[2:3], v[220:221], v[18:19]
	v_pk_mul_f32 v[18:19], v[62:63], v[16:17] op_sel_hi:[1,0]
	v_cvt_pk_bf16_f32 v2, v2, v3
	v_pk_mul_f32 v[4:5], v[222:223], v[18:19]
	v_pk_mul_f32 v[18:19], v[22:23], v[16:17] op_sel_hi:[1,0]
	v_cvt_pk_bf16_f32 v3, v4, v5
	global_store_dwordx2 v[14:15], v[2:3], off offset:1088
	s_waitcnt vmcnt(6)
	v_pk_mul_f32 v[2:3], v[224:225], v[18:19]
	v_pk_mul_f32 v[4:5], v[226:227], v[20:21]
	v_cvt_pk_bf16_f32 v2, v2, v3
	v_cvt_pk_bf16_f32 v3, v4, v5
	global_store_dwordx2 v[14:15], v[2:3], off offset:1120
	s_waitcnt vmcnt(6)
	v_pk_mul_f32 v[2:3], v[228:229], v[10:11]
	v_pk_mul_f32 v[4:5], v[230:231], v[12:13]
	v_cvt_pk_bf16_f32 v2, v2, v3
	v_cvt_pk_bf16_f32 v3, v4, v5
	global_store_dwordx2 v[14:15], v[2:3], off offset:1152
	s_waitcnt vmcnt(6)
	v_pk_mul_f32 v[2:3], v[232:233], v[6:7]
	v_pk_mul_f32 v[4:5], v[234:235], v[8:9]
	v_cvt_pk_bf16_f32 v2, v2, v3
	v_cvt_pk_bf16_f32 v3, v4, v5
	global_store_dwordx2 v[14:15], v[2:3], off offset:1184
	v_pk_mul_f32 v[6:7], v[26:27], v[16:17] op_sel_hi:[1,0]
	v_pk_mul_f32 v[8:9], v[56:57], v[16:17] op_sel_hi:[1,0]
	s_waitcnt vmcnt(6)
	v_pk_mul_f32 v[2:3], v[236:237], v[6:7]
	v_pk_mul_f32 v[4:5], v[238:239], v[8:9]
	v_cvt_pk_bf16_f32 v2, v2, v3
	v_cvt_pk_bf16_f32 v3, v4, v5
	global_store_dwordx2 v[14:15], v[2:3], off offset:1216
	v_pk_mul_f32 v[6:7], v[46:47], v[16:17] op_sel_hi:[1,0]
	v_pk_mul_f32 v[8:9], v[48:49], v[16:17] op_sel_hi:[1,0]
	s_waitcnt vmcnt(6)
	v_pk_mul_f32 v[2:3], v[6:7], v[240:241]
	v_pk_mul_f32 v[4:5], v[8:9], v[242:243]
	v_cvt_pk_bf16_f32 v2, v2, v3
	v_cvt_pk_bf16_f32 v3, v4, v5
	global_store_dwordx2 v[14:15], v[2:3], off offset:1248
	s_waitcnt vmcnt(0) lgkmcnt(0)
	s_barrier
	s_cbranch_scc1 .LBB0_540
